# attention epilogue: adjacent lanes paired with v_cndmask_b32_dpp so the bf16 output tile is written with 32 dword stores per lane instead of 64 two-byte stores (same values); pads keep later code plac
# speedup vs baseline: 1.2829x; 1.2829x over previous
; __device__ __forceinline__ int crow(int r, int hi) { return (r & 3) + 8 * (r >> 2) + 4 * hi; }
; __device__ __forceinline__ unsigned cvtpk(float lo, float hi) { unsigned r; asm volatile("v_cvt_pk_bf16_f32 %0, %1, %2" : "=v"(r) : "v"(lo), "v"(hi)); return r; }
; template <int DKR, int LDQ, int LDK, int LDV, int LDO> ...
;     ...
;   if (hi == 0) li_l[r32] = l_reg; asm volatile("s_waitcnt lgkmcnt(0)" ::: "memory");
;   float rli[16];
; #pragma unroll
;   for (int r = 0; r < 16; ++r) rli[r] = __builtin_amdgcn_rcpf(li_l[crow(r, hi)]);
;   bf16_t* Ow = Ob + (long)(wid * QBLK) * LDO;
; #pragma unroll
;   for (int r = 0; r < 16; ++r) { int orow = crow(r, hi);
; #pragma unroll
;     for (int d0 = 0; d0 < 4; ++d0) Ow[(long)orow * LDO + d0 * 32 + r32] = (bf16_t)(cvtpk(o[d0][r] * rli[r], 0.f) & 0xffffu); }
.LBB0_595:
	s_or_b64 exec, exec, s[0:1]
	s_waitcnt lgkmcnt(0)
	v_add_u32_e32 v72, v135, v132
	ds_read_b128 v[68:71], v72
	ds_read_b128 v[74:77], v72 offset:32
	ds_read_b128 v[78:81], v72 offset:64
	ds_read_b128 v[82:85], v72 offset:96
	s_add_u32 s0, s29, s36
	v_ashrrev_i32_e32 v135, 31, v134
	s_addc_u32 s1, s40, s37
	v_lshlrev_b64 v[64:65], 12, v[134:135]
	v_lshl_add_u64 v[64:65], s[0:1], 0, v[64:65]
	v_lshlrev_b32_e32 v132, 1, v145
	v_lshlrev_b32_e32 v66, 14, v146
	v_lshl_add_u64 v[64:65], v[64:65], 0, v[132:133]
	v_mov_b32_e32 v67, v133
	v_lshl_add_u64 v[64:65], v[64:65], 0, v[66:67]
	v_mbcnt_lo_u32_b32 v90, -1, 0
	v_mbcnt_hi_u32_b32 v90, -1, v90
	v_and_b32_e32 v90, 1, v90
	v_mul_u32_u24_e32 v90, 0xffe, v90
	v_mov_b32_e32 v91, 0
	v_lshl_add_u64 v[86:87], v[64:65], 0, v[90:91]
	s_waitcnt lgkmcnt(0)
	v_rcp_f32_e32 v68, v68
	v_rcp_f32_e32 v69, v69
	v_rcp_f32_e32 v70, v70
	v_rcp_f32_e32 v71, v71
	v_rcp_f32_e32 v74, v74
	v_rcp_f32_e32 v75, v75
	v_rcp_f32_e32 v76, v76
	v_rcp_f32_e32 v77, v77
	v_rcp_f32_e32 v78, v78
	v_rcp_f32_e32 v79, v79
	v_rcp_f32_e32 v80, v80
	v_rcp_f32_e32 v81, v81
	v_rcp_f32_e32 v82, v82
	v_rcp_f32_e32 v83, v83
	v_rcp_f32_e32 v84, v84
	v_rcp_f32_e32 v85, v85
	s_mov_b32 vcc_lo, 0xaaaaaaaa
	s_mov_b32 vcc_hi, 0xaaaaaaaa
	s_nop 1
	v_cndmask_b32_e32 v92, v68, v69, vcc
	v_cndmask_b32_e32 v94, v70, v71, vcc
	v_cndmask_b32_e32 v96, v74, v75, vcc
	v_cndmask_b32_e32 v98, v76, v77, vcc
	v_cndmask_b32_e32 v100, v78, v79, vcc
	v_cndmask_b32_e32 v102, v80, v81, vcc
	v_cndmask_b32_e32 v104, v82, v83, vcc
	v_cndmask_b32_e32 v106, v84, v85, vcc
	v_lshl_add_u64 v[88:89], v[86:87], 0, 0
	s_mov_b32 vcc_lo, 0x55555555
	s_mov_b32 vcc_hi, 0x55555555
	s_nop 1
	v_cndmask_b32_dpp v108, v1, v0, vcc quad_perm:[1,0,3,2] row_mask:0xf bank_mask:0xf
	v_cndmask_b32_dpp v110, v49, v48, vcc quad_perm:[1,0,3,2] row_mask:0xf bank_mask:0xf
	v_cndmask_b32_dpp v112, v33, v32, vcc quad_perm:[1,0,3,2] row_mask:0xf bank_mask:0xf
	v_cndmask_b32_dpp v114, v17, v16, vcc quad_perm:[1,0,3,2] row_mask:0xf bank_mask:0xf
	s_mov_b32 vcc_lo, 0xaaaaaaaa
	s_mov_b32 vcc_hi, 0xaaaaaaaa
	s_nop 1
	v_cndmask_b32_dpp v109, v0, v1, vcc quad_perm:[1,0,3,2] row_mask:0xf bank_mask:0xf
	v_cndmask_b32_dpp v111, v48, v49, vcc quad_perm:[1,0,3,2] row_mask:0xf bank_mask:0xf
	v_cndmask_b32_dpp v113, v32, v33, vcc quad_perm:[1,0,3,2] row_mask:0xf bank_mask:0xf
	v_cndmask_b32_dpp v115, v16, v17, vcc quad_perm:[1,0,3,2] row_mask:0xf bank_mask:0xf
	v_pk_mul_f32 v[108:109], v[108:109], v[92:93] op_sel_hi:[1,0]
	v_pk_mul_f32 v[110:111], v[110:111], v[92:93] op_sel_hi:[1,0]
	v_pk_mul_f32 v[112:113], v[112:113], v[92:93] op_sel_hi:[1,0]
	v_pk_mul_f32 v[114:115], v[114:115], v[92:93] op_sel_hi:[1,0]
	v_cvt_pk_bf16_f32 v73, v108, v109
	v_cvt_pk_bf16_f32 v116, v110, v111
	v_cvt_pk_bf16_f32 v117, v112, v113
	v_cvt_pk_bf16_f32 v118, v114, v115
	global_store_dword v[88:89], v73, off
	global_store_dword v[88:89], v116, off offset:64
	global_store_dword v[88:89], v117, off offset:128
	global_store_dword v[88:89], v118, off offset:192
	s_mov_b64 s[0:1], 0x2000
	v_lshl_add_u64 v[88:89], v[86:87], 0, s[0:1]
	s_mov_b32 vcc_lo, 0x55555555
	s_mov_b32 vcc_hi, 0x55555555
	s_nop 1
	v_cndmask_b32_dpp v108, v3, v2, vcc quad_perm:[1,0,3,2] row_mask:0xf bank_mask:0xf
	v_cndmask_b32_dpp v110, v51, v50, vcc quad_perm:[1,0,3,2] row_mask:0xf bank_mask:0xf
	v_cndmask_b32_dpp v112, v35, v34, vcc quad_perm:[1,0,3,2] row_mask:0xf bank_mask:0xf
	v_cndmask_b32_dpp v114, v19, v18, vcc quad_perm:[1,0,3,2] row_mask:0xf bank_mask:0xf
	s_mov_b32 vcc_lo, 0xaaaaaaaa
	s_mov_b32 vcc_hi, 0xaaaaaaaa
	s_nop 1
	v_cndmask_b32_dpp v109, v2, v3, vcc quad_perm:[1,0,3,2] row_mask:0xf bank_mask:0xf
	v_cndmask_b32_dpp v111, v50, v51, vcc quad_perm:[1,0,3,2] row_mask:0xf bank_mask:0xf
	v_cndmask_b32_dpp v113, v34, v35, vcc quad_perm:[1,0,3,2] row_mask:0xf bank_mask:0xf
	v_cndmask_b32_dpp v115, v18, v19, vcc quad_perm:[1,0,3,2] row_mask:0xf bank_mask:0xf
	v_pk_mul_f32 v[108:109], v[108:109], v[94:95] op_sel_hi:[1,0]
	v_pk_mul_f32 v[110:111], v[110:111], v[94:95] op_sel_hi:[1,0]
	v_pk_mul_f32 v[112:113], v[112:113], v[94:95] op_sel_hi:[1,0]
	v_pk_mul_f32 v[114:115], v[114:115], v[94:95] op_sel_hi:[1,0]
	v_cvt_pk_bf16_f32 v73, v108, v109
	v_cvt_pk_bf16_f32 v116, v110, v111
	v_cvt_pk_bf16_f32 v117, v112, v113
	v_cvt_pk_bf16_f32 v118, v114, v115
	global_store_dword v[88:89], v73, off
	global_store_dword v[88:89], v116, off offset:64
	global_store_dword v[88:89], v117, off offset:128
	global_store_dword v[88:89], v118, off offset:192
	s_mov_b64 s[0:1], 0x8000
	v_lshl_add_u64 v[88:89], v[86:87], 0, s[0:1]
	s_mov_b32 vcc_lo, 0x55555555
	s_mov_b32 vcc_hi, 0x55555555
	s_nop 1
	v_cndmask_b32_dpp v108, v5, v4, vcc quad_perm:[1,0,3,2] row_mask:0xf bank_mask:0xf
	v_cndmask_b32_dpp v110, v53, v52, vcc quad_perm:[1,0,3,2] row_mask:0xf bank_mask:0xf
	v_cndmask_b32_dpp v112, v37, v36, vcc quad_perm:[1,0,3,2] row_mask:0xf bank_mask:0xf
	v_cndmask_b32_dpp v114, v21, v20, vcc quad_perm:[1,0,3,2] row_mask:0xf bank_mask:0xf
	s_mov_b32 vcc_lo, 0xaaaaaaaa
	s_mov_b32 vcc_hi, 0xaaaaaaaa
	s_nop 1
	v_cndmask_b32_dpp v109, v4, v5, vcc quad_perm:[1,0,3,2] row_mask:0xf bank_mask:0xf
	v_cndmask_b32_dpp v111, v52, v53, vcc quad_perm:[1,0,3,2] row_mask:0xf bank_mask:0xf
	v_cndmask_b32_dpp v113, v36, v37, vcc quad_perm:[1,0,3,2] row_mask:0xf bank_mask:0xf
	v_cndmask_b32_dpp v115, v20, v21, vcc quad_perm:[1,0,3,2] row_mask:0xf bank_mask:0xf
	v_pk_mul_f32 v[108:109], v[108:109], v[96:97] op_sel_hi:[1,0]
	v_pk_mul_f32 v[110:111], v[110:111], v[96:97] op_sel_hi:[1,0]
	v_pk_mul_f32 v[112:113], v[112:113], v[96:97] op_sel_hi:[1,0]
	v_pk_mul_f32 v[114:115], v[114:115], v[96:97] op_sel_hi:[1,0]
; __device__ __forceinline__ int crow(int r, int hi) { return (r & 3) + 8 * (r >> 2) + 4 * hi; }
; __device__ __forceinline__ unsigned cvtpk(float lo, float hi) { unsigned r; asm volatile("v_cvt_pk_bf16_f32 %0, %1, %2" : "=v"(r) : "v"(lo), "v"(hi)); return r; }
; template <int DKR, int LDQ, int LDK, int LDV, int LDO> ...
;     ...
;   for (int r = 0; r < 16; ++r) { int orow = crow(r, hi);
; #pragma unroll
;     for (int d0 = 0; d0 < 4; ++d0) Ow[(long)orow * LDO + d0 * 32 + r32] = (bf16_t)(cvtpk(o[d0][r] * rli[r], 0.f) & 0xffffu); }
	v_cvt_pk_bf16_f32 v73, v108, v109
	v_cvt_pk_bf16_f32 v116, v110, v111
	v_cvt_pk_bf16_f32 v117, v112, v113
	v_cvt_pk_bf16_f32 v118, v114, v115
	global_store_dword v[88:89], v73, off
	global_store_dword v[88:89], v116, off offset:64
	global_store_dword v[88:89], v117, off offset:128
	global_store_dword v[88:89], v118, off offset:192
	s_mov_b64 s[0:1], 0xa000
	v_lshl_add_u64 v[88:89], v[86:87], 0, s[0:1]
	s_mov_b32 vcc_lo, 0x55555555
	s_mov_b32 vcc_hi, 0x55555555
	s_nop 1
	v_cndmask_b32_dpp v108, v7, v6, vcc quad_perm:[1,0,3,2] row_mask:0xf bank_mask:0xf
	v_cndmask_b32_dpp v110, v55, v54, vcc quad_perm:[1,0,3,2] row_mask:0xf bank_mask:0xf
	v_cndmask_b32_dpp v112, v39, v38, vcc quad_perm:[1,0,3,2] row_mask:0xf bank_mask:0xf
	v_cndmask_b32_dpp v114, v23, v22, vcc quad_perm:[1,0,3,2] row_mask:0xf bank_mask:0xf
	s_mov_b32 vcc_lo, 0xaaaaaaaa
	s_mov_b32 vcc_hi, 0xaaaaaaaa
	s_nop 1
	v_cndmask_b32_dpp v109, v6, v7, vcc quad_perm:[1,0,3,2] row_mask:0xf bank_mask:0xf
	v_cndmask_b32_dpp v111, v54, v55, vcc quad_perm:[1,0,3,2] row_mask:0xf bank_mask:0xf
	v_cndmask_b32_dpp v113, v38, v39, vcc quad_perm:[1,0,3,2] row_mask:0xf bank_mask:0xf
	v_cndmask_b32_dpp v115, v22, v23, vcc quad_perm:[1,0,3,2] row_mask:0xf bank_mask:0xf
	v_pk_mul_f32 v[108:109], v[108:109], v[98:99] op_sel_hi:[1,0]
	v_pk_mul_f32 v[110:111], v[110:111], v[98:99] op_sel_hi:[1,0]
	v_pk_mul_f32 v[112:113], v[112:113], v[98:99] op_sel_hi:[1,0]
	v_pk_mul_f32 v[114:115], v[114:115], v[98:99] op_sel_hi:[1,0]
	v_cvt_pk_bf16_f32 v73, v108, v109
	v_cvt_pk_bf16_f32 v116, v110, v111
	v_cvt_pk_bf16_f32 v117, v112, v113
	v_cvt_pk_bf16_f32 v118, v114, v115
	global_store_dword v[88:89], v73, off
	global_store_dword v[88:89], v116, off offset:64
	global_store_dword v[88:89], v117, off offset:128
	global_store_dword v[88:89], v118, off offset:192
	s_mov_b64 s[0:1], 0x10000
	v_lshl_add_u64 v[88:89], v[86:87], 0, s[0:1]
	s_mov_b32 vcc_lo, 0x55555555
	s_mov_b32 vcc_hi, 0x55555555
	s_nop 1
	v_cndmask_b32_dpp v108, v9, v8, vcc quad_perm:[1,0,3,2] row_mask:0xf bank_mask:0xf
	v_cndmask_b32_dpp v110, v57, v56, vcc quad_perm:[1,0,3,2] row_mask:0xf bank_mask:0xf
	v_cndmask_b32_dpp v112, v41, v40, vcc quad_perm:[1,0,3,2] row_mask:0xf bank_mask:0xf
	v_cndmask_b32_dpp v114, v25, v24, vcc quad_perm:[1,0,3,2] row_mask:0xf bank_mask:0xf
	s_mov_b32 vcc_lo, 0xaaaaaaaa
	s_mov_b32 vcc_hi, 0xaaaaaaaa
	s_nop 1
	v_cndmask_b32_dpp v109, v8, v9, vcc quad_perm:[1,0,3,2] row_mask:0xf bank_mask:0xf
	v_cndmask_b32_dpp v111, v56, v57, vcc quad_perm:[1,0,3,2] row_mask:0xf bank_mask:0xf
	v_cndmask_b32_dpp v113, v40, v41, vcc quad_perm:[1,0,3,2] row_mask:0xf bank_mask:0xf
	v_cndmask_b32_dpp v115, v24, v25, vcc quad_perm:[1,0,3,2] row_mask:0xf bank_mask:0xf
	v_pk_mul_f32 v[108:109], v[108:109], v[100:101] op_sel_hi:[1,0]
	v_pk_mul_f32 v[110:111], v[110:111], v[100:101] op_sel_hi:[1,0]
	v_pk_mul_f32 v[112:113], v[112:113], v[100:101] op_sel_hi:[1,0]
	v_pk_mul_f32 v[114:115], v[114:115], v[100:101] op_sel_hi:[1,0]
	v_cvt_pk_bf16_f32 v73, v108, v109
	v_cvt_pk_bf16_f32 v116, v110, v111
	v_cvt_pk_bf16_f32 v117, v112, v113
	v_cvt_pk_bf16_f32 v118, v114, v115
	global_store_dword v[88:89], v73, off
	global_store_dword v[88:89], v116, off offset:64
	global_store_dword v[88:89], v117, off offset:128
	global_store_dword v[88:89], v118, off offset:192
	s_mov_b64 s[0:1], 0x12000
	v_lshl_add_u64 v[88:89], v[86:87], 0, s[0:1]
	s_mov_b32 vcc_lo, 0x55555555
	s_mov_b32 vcc_hi, 0x55555555
	s_nop 1
	v_cndmask_b32_dpp v108, v11, v10, vcc quad_perm:[1,0,3,2] row_mask:0xf bank_mask:0xf
	v_cndmask_b32_dpp v110, v59, v58, vcc quad_perm:[1,0,3,2] row_mask:0xf bank_mask:0xf
	v_cndmask_b32_dpp v112, v43, v42, vcc quad_perm:[1,0,3,2] row_mask:0xf bank_mask:0xf
	v_cndmask_b32_dpp v114, v27, v26, vcc quad_perm:[1,0,3,2] row_mask:0xf bank_mask:0xf
	s_mov_b32 vcc_lo, 0xaaaaaaaa
	s_mov_b32 vcc_hi, 0xaaaaaaaa
	s_nop 1
	v_cndmask_b32_dpp v109, v10, v11, vcc quad_perm:[1,0,3,2] row_mask:0xf bank_mask:0xf
; __device__ __forceinline__ int crow(int r, int hi) { return (r & 3) + 8 * (r >> 2) + 4 * hi; }
; __device__ __forceinline__ unsigned cvtpk(float lo, float hi) { unsigned r; asm volatile("v_cvt_pk_bf16_f32 %0, %1, %2" : "=v"(r) : "v"(lo), "v"(hi)); return r; }
; template <int DKR, int LDQ, int LDK, int LDV, int LDO> ...
;     ...
;   for (int r = 0; r < 16; ++r) { int orow = crow(r, hi);
; #pragma unroll
;     for (int d0 = 0; d0 < 4; ++d0) Ow[(long)orow * LDO + d0 * 32 + r32] = (bf16_t)(cvtpk(o[d0][r] * rli[r], 0.f) & 0xffffu); }
;   __syncthreads();
	v_cndmask_b32_dpp v111, v58, v59, vcc quad_perm:[1,0,3,2] row_mask:0xf bank_mask:0xf
	v_cndmask_b32_dpp v113, v42, v43, vcc quad_perm:[1,0,3,2] row_mask:0xf bank_mask:0xf
	v_cndmask_b32_dpp v115, v26, v27, vcc quad_perm:[1,0,3,2] row_mask:0xf bank_mask:0xf
	v_pk_mul_f32 v[108:109], v[108:109], v[102:103] op_sel_hi:[1,0]
	v_pk_mul_f32 v[110:111], v[110:111], v[102:103] op_sel_hi:[1,0]
	v_pk_mul_f32 v[112:113], v[112:113], v[102:103] op_sel_hi:[1,0]
	v_pk_mul_f32 v[114:115], v[114:115], v[102:103] op_sel_hi:[1,0]
	v_cvt_pk_bf16_f32 v73, v108, v109
	v_cvt_pk_bf16_f32 v116, v110, v111
	v_cvt_pk_bf16_f32 v117, v112, v113
	v_cvt_pk_bf16_f32 v118, v114, v115
	global_store_dword v[88:89], v73, off
	global_store_dword v[88:89], v116, off offset:64
	global_store_dword v[88:89], v117, off offset:128
	global_store_dword v[88:89], v118, off offset:192
	s_mov_b64 s[0:1], 0x18000
	v_lshl_add_u64 v[88:89], v[86:87], 0, s[0:1]
	s_mov_b32 vcc_lo, 0x55555555
	s_mov_b32 vcc_hi, 0x55555555
	s_nop 1
	v_cndmask_b32_dpp v108, v13, v12, vcc quad_perm:[1,0,3,2] row_mask:0xf bank_mask:0xf
	v_cndmask_b32_dpp v110, v61, v60, vcc quad_perm:[1,0,3,2] row_mask:0xf bank_mask:0xf
	v_cndmask_b32_dpp v112, v45, v44, vcc quad_perm:[1,0,3,2] row_mask:0xf bank_mask:0xf
	v_cndmask_b32_dpp v114, v29, v28, vcc quad_perm:[1,0,3,2] row_mask:0xf bank_mask:0xf
	s_mov_b32 vcc_lo, 0xaaaaaaaa
	s_mov_b32 vcc_hi, 0xaaaaaaaa
	s_nop 1
	v_cndmask_b32_dpp v109, v12, v13, vcc quad_perm:[1,0,3,2] row_mask:0xf bank_mask:0xf
	v_cndmask_b32_dpp v111, v60, v61, vcc quad_perm:[1,0,3,2] row_mask:0xf bank_mask:0xf
	v_cndmask_b32_dpp v113, v44, v45, vcc quad_perm:[1,0,3,2] row_mask:0xf bank_mask:0xf
	v_cndmask_b32_dpp v115, v28, v29, vcc quad_perm:[1,0,3,2] row_mask:0xf bank_mask:0xf
	v_pk_mul_f32 v[108:109], v[108:109], v[104:105] op_sel_hi:[1,0]
	v_pk_mul_f32 v[110:111], v[110:111], v[104:105] op_sel_hi:[1,0]
	v_pk_mul_f32 v[112:113], v[112:113], v[104:105] op_sel_hi:[1,0]
	v_pk_mul_f32 v[114:115], v[114:115], v[104:105] op_sel_hi:[1,0]
	v_cvt_pk_bf16_f32 v73, v108, v109
	v_cvt_pk_bf16_f32 v116, v110, v111
	v_cvt_pk_bf16_f32 v117, v112, v113
	v_cvt_pk_bf16_f32 v118, v114, v115
	global_store_dword v[88:89], v73, off
	global_store_dword v[88:89], v116, off offset:64
	global_store_dword v[88:89], v117, off offset:128
	global_store_dword v[88:89], v118, off offset:192
	s_mov_b64 s[0:1], 0x1a000
	v_lshl_add_u64 v[88:89], v[86:87], 0, s[0:1]
	s_mov_b32 vcc_lo, 0x55555555
	s_mov_b32 vcc_hi, 0x55555555
	s_nop 1
	v_cndmask_b32_dpp v108, v15, v14, vcc quad_perm:[1,0,3,2] row_mask:0xf bank_mask:0xf
	v_cndmask_b32_dpp v110, v63, v62, vcc quad_perm:[1,0,3,2] row_mask:0xf bank_mask:0xf
	v_cndmask_b32_dpp v112, v47, v46, vcc quad_perm:[1,0,3,2] row_mask:0xf bank_mask:0xf
	v_cndmask_b32_dpp v114, v31, v30, vcc quad_perm:[1,0,3,2] row_mask:0xf bank_mask:0xf
	s_mov_b32 vcc_lo, 0xaaaaaaaa
	s_mov_b32 vcc_hi, 0xaaaaaaaa
	s_nop 1
	v_cndmask_b32_dpp v109, v14, v15, vcc quad_perm:[1,0,3,2] row_mask:0xf bank_mask:0xf
	v_cndmask_b32_dpp v111, v62, v63, vcc quad_perm:[1,0,3,2] row_mask:0xf bank_mask:0xf
	v_cndmask_b32_dpp v113, v46, v47, vcc quad_perm:[1,0,3,2] row_mask:0xf bank_mask:0xf
	v_cndmask_b32_dpp v115, v30, v31, vcc quad_perm:[1,0,3,2] row_mask:0xf bank_mask:0xf
	v_pk_mul_f32 v[108:109], v[108:109], v[106:107] op_sel_hi:[1,0]
	v_pk_mul_f32 v[110:111], v[110:111], v[106:107] op_sel_hi:[1,0]
	v_pk_mul_f32 v[112:113], v[112:113], v[106:107] op_sel_hi:[1,0]
	v_pk_mul_f32 v[114:115], v[114:115], v[106:107] op_sel_hi:[1,0]
	v_cvt_pk_bf16_f32 v73, v108, v109
	v_cvt_pk_bf16_f32 v116, v110, v111
	v_cvt_pk_bf16_f32 v117, v112, v113
	v_cvt_pk_bf16_f32 v118, v114, v115
	global_store_dword v[88:89], v73, off
	global_store_dword v[88:89], v116, off offset:64
	global_store_dword v[88:89], v117, off offset:128
	global_store_dword v[88:89], v118, off offset:192
	s_mov_b32 s2, 4
	s_andn2_b64 vcc, exec, s[14:15]
	s_mov_b64 s[0:1], 0
	s_nop 0
	s_nop 0
	s_nop 0
	s_nop 0
	s_waitcnt vmcnt(63) expcnt(7) lgkmcnt(15)
	s_barrier
	s_cbranch_vccz .LBB0_613

; __device__ __forceinline__ int crow(int r, int hi) { return (r & 3) + 8 * (r >> 2) + 4 * hi; }
; __device__ __forceinline__ unsigned cvtpk(float lo, float hi) { unsigned r; asm volatile("v_cvt_pk_bf16_f32 %0, %1, %2" : "=v"(r) : "v"(lo), "v"(hi)); return r; }
; template <int DKR, int LDQ, int LDK, int LDV, int LDO> ...
;     ...
;   if (hi == 0) li_l[r32] = l_reg; asm volatile("s_waitcnt lgkmcnt(0)" ::: "memory");
;   float rli[16];
; #pragma unroll
;   for (int r = 0; r < 16; ++r) rli[r] = __builtin_amdgcn_rcpf(li_l[crow(r, hi)]);
;   bf16_t* Ow = Ob + (long)(wid * QBLK) * LDO;
; #pragma unroll
;   for (int r = 0; r < 16; ++r) { int orow = crow(r, hi);
; #pragma unroll
;     for (int d0 = 0; d0 < 4; ++d0) Ow[(long)orow * LDO + d0 * 32 + r32] = (bf16_t)(cvtpk(o[d0][r] * rli[r], 0.f) & 0xffffu); }
.LBB0_614:
	s_or_b64 exec, exec, s[0:1]
	s_waitcnt lgkmcnt(0)
	v_add_u32_e32 v72, v179, v176
	ds_read_b128 v[68:71], v72
	ds_read_b128 v[74:77], v72 offset:32
	ds_read_b128 v[78:81], v72 offset:64
	ds_read_b128 v[82:85], v72 offset:96
	s_add_u32 s0, s29, s12
	v_ashrrev_i32_e32 v179, 31, v178
	s_addc_u32 s1, s40, s13
	v_lshlrev_b64 v[64:65], 12, v[178:179]
	v_lshl_add_u64 v[64:65], s[0:1], 0, v[64:65]
	v_lshlrev_b32_e32 v176, 1, v184
	v_lshlrev_b32_e32 v66, 14, v183
	v_lshl_add_u64 v[64:65], v[64:65], 0, v[176:177]
	v_mov_b32_e32 v67, v177
	v_lshl_add_u64 v[64:65], v[64:65], 0, v[66:67]
	v_mbcnt_lo_u32_b32 v90, -1, 0
	v_mbcnt_hi_u32_b32 v90, -1, v90
	v_and_b32_e32 v90, 1, v90
	v_mul_u32_u24_e32 v90, 0xffe, v90
	v_mov_b32_e32 v91, 0
	v_lshl_add_u64 v[86:87], v[64:65], 0, v[90:91]
	s_waitcnt lgkmcnt(0)
	v_rcp_f32_e32 v68, v68
	v_rcp_f32_e32 v69, v69
	v_rcp_f32_e32 v70, v70
	v_rcp_f32_e32 v71, v71
	v_rcp_f32_e32 v74, v74
	v_rcp_f32_e32 v75, v75
	v_rcp_f32_e32 v76, v76
	v_rcp_f32_e32 v77, v77
	v_rcp_f32_e32 v78, v78
	v_rcp_f32_e32 v79, v79
	v_rcp_f32_e32 v80, v80
	v_rcp_f32_e32 v81, v81
	v_rcp_f32_e32 v82, v82
	v_rcp_f32_e32 v83, v83
	v_rcp_f32_e32 v84, v84
	v_rcp_f32_e32 v85, v85
	s_mov_b32 vcc_lo, 0xaaaaaaaa
	s_mov_b32 vcc_hi, 0xaaaaaaaa
	s_nop 1
	v_cndmask_b32_e32 v92, v68, v69, vcc
	v_cndmask_b32_e32 v94, v70, v71, vcc
	v_cndmask_b32_e32 v96, v74, v75, vcc
	v_cndmask_b32_e32 v98, v76, v77, vcc
	v_cndmask_b32_e32 v100, v78, v79, vcc
	v_cndmask_b32_e32 v102, v80, v81, vcc
	v_cndmask_b32_e32 v104, v82, v83, vcc
	v_cndmask_b32_e32 v106, v84, v85, vcc
	v_lshl_add_u64 v[88:89], v[86:87], 0, 0
	s_mov_b32 vcc_lo, 0x55555555
	s_mov_b32 vcc_hi, 0x55555555
	s_nop 1
	v_cndmask_b32_dpp v108, v1, v0, vcc quad_perm:[1,0,3,2] row_mask:0xf bank_mask:0xf
	v_cndmask_b32_dpp v110, v49, v48, vcc quad_perm:[1,0,3,2] row_mask:0xf bank_mask:0xf
	v_cndmask_b32_dpp v112, v33, v32, vcc quad_perm:[1,0,3,2] row_mask:0xf bank_mask:0xf
	v_cndmask_b32_dpp v114, v17, v16, vcc quad_perm:[1,0,3,2] row_mask:0xf bank_mask:0xf
	s_mov_b32 vcc_lo, 0xaaaaaaaa
	s_mov_b32 vcc_hi, 0xaaaaaaaa
	s_nop 1
	v_cndmask_b32_dpp v109, v0, v1, vcc quad_perm:[1,0,3,2] row_mask:0xf bank_mask:0xf
	v_cndmask_b32_dpp v111, v48, v49, vcc quad_perm:[1,0,3,2] row_mask:0xf bank_mask:0xf
	v_cndmask_b32_dpp v113, v32, v33, vcc quad_perm:[1,0,3,2] row_mask:0xf bank_mask:0xf
	v_cndmask_b32_dpp v115, v16, v17, vcc quad_perm:[1,0,3,2] row_mask:0xf bank_mask:0xf
	v_pk_mul_f32 v[108:109], v[108:109], v[92:93] op_sel_hi:[1,0]
	v_pk_mul_f32 v[110:111], v[110:111], v[92:93] op_sel_hi:[1,0]
	v_pk_mul_f32 v[112:113], v[112:113], v[92:93] op_sel_hi:[1,0]
	v_pk_mul_f32 v[114:115], v[114:115], v[92:93] op_sel_hi:[1,0]
	v_cvt_pk_bf16_f32 v73, v108, v109
	v_cvt_pk_bf16_f32 v116, v110, v111
	v_cvt_pk_bf16_f32 v117, v112, v113
	v_cvt_pk_bf16_f32 v118, v114, v115
	global_store_dword v[88:89], v73, off offset:2048
	global_store_dword v[88:89], v116, off offset:2112
	global_store_dword v[88:89], v117, off offset:2176
	global_store_dword v[88:89], v118, off offset:2240
	s_mov_b64 s[0:1], 0x2000
	v_lshl_add_u64 v[88:89], v[86:87], 0, s[0:1]
	s_mov_b32 vcc_lo, 0x55555555
	s_mov_b32 vcc_hi, 0x55555555
	s_nop 1
	v_cndmask_b32_dpp v108, v3, v2, vcc quad_perm:[1,0,3,2] row_mask:0xf bank_mask:0xf
	v_cndmask_b32_dpp v110, v51, v50, vcc quad_perm:[1,0,3,2] row_mask:0xf bank_mask:0xf
	v_cndmask_b32_dpp v112, v35, v34, vcc quad_perm:[1,0,3,2] row_mask:0xf bank_mask:0xf
	v_cndmask_b32_dpp v114, v19, v18, vcc quad_perm:[1,0,3,2] row_mask:0xf bank_mask:0xf
	s_mov_b32 vcc_lo, 0xaaaaaaaa
	s_mov_b32 vcc_hi, 0xaaaaaaaa
	s_nop 1
	v_cndmask_b32_dpp v109, v2, v3, vcc quad_perm:[1,0,3,2] row_mask:0xf bank_mask:0xf
	v_cndmask_b32_dpp v111, v50, v51, vcc quad_perm:[1,0,3,2] row_mask:0xf bank_mask:0xf
	v_cndmask_b32_dpp v113, v34, v35, vcc quad_perm:[1,0,3,2] row_mask:0xf bank_mask:0xf
	v_cndmask_b32_dpp v115, v18, v19, vcc quad_perm:[1,0,3,2] row_mask:0xf bank_mask:0xf
	v_pk_mul_f32 v[108:109], v[108:109], v[94:95] op_sel_hi:[1,0]
	v_pk_mul_f32 v[110:111], v[110:111], v[94:95] op_sel_hi:[1,0]
	v_pk_mul_f32 v[112:113], v[112:113], v[94:95] op_sel_hi:[1,0]
	v_pk_mul_f32 v[114:115], v[114:115], v[94:95] op_sel_hi:[1,0]
	v_cvt_pk_bf16_f32 v73, v108, v109
	v_cvt_pk_bf16_f32 v116, v110, v111
	v_cvt_pk_bf16_f32 v117, v112, v113
	v_cvt_pk_bf16_f32 v118, v114, v115
	global_store_dword v[88:89], v73, off offset:2048
	global_store_dword v[88:89], v116, off offset:2112
	global_store_dword v[88:89], v117, off offset:2176
	global_store_dword v[88:89], v118, off offset:2240
	s_mov_b64 s[0:1], 0x8000
	v_lshl_add_u64 v[88:89], v[86:87], 0, s[0:1]
	s_mov_b32 vcc_lo, 0x55555555
	s_mov_b32 vcc_hi, 0x55555555
	s_nop 1
	v_cndmask_b32_dpp v108, v5, v4, vcc quad_perm:[1,0,3,2] row_mask:0xf bank_mask:0xf
	v_cndmask_b32_dpp v110, v53, v52, vcc quad_perm:[1,0,3,2] row_mask:0xf bank_mask:0xf
	v_cndmask_b32_dpp v112, v37, v36, vcc quad_perm:[1,0,3,2] row_mask:0xf bank_mask:0xf
	v_cndmask_b32_dpp v114, v21, v20, vcc quad_perm:[1,0,3,2] row_mask:0xf bank_mask:0xf
	s_mov_b32 vcc_lo, 0xaaaaaaaa
	s_mov_b32 vcc_hi, 0xaaaaaaaa
	s_nop 1
	v_cndmask_b32_dpp v109, v4, v5, vcc quad_perm:[1,0,3,2] row_mask:0xf bank_mask:0xf
	v_cndmask_b32_dpp v111, v52, v53, vcc quad_perm:[1,0,3,2] row_mask:0xf bank_mask:0xf
	v_cndmask_b32_dpp v113, v36, v37, vcc quad_perm:[1,0,3,2] row_mask:0xf bank_mask:0xf
	v_cndmask_b32_dpp v115, v20, v21, vcc quad_perm:[1,0,3,2] row_mask:0xf bank_mask:0xf
	v_pk_mul_f32 v[108:109], v[108:109], v[96:97] op_sel_hi:[1,0]
	v_pk_mul_f32 v[110:111], v[110:111], v[96:97] op_sel_hi:[1,0]
	v_pk_mul_f32 v[112:113], v[112:113], v[96:97] op_sel_hi:[1,0]
; __device__ __forceinline__ int crow(int r, int hi) { return (r & 3) + 8 * (r >> 2) + 4 * hi; }
; __device__ __forceinline__ unsigned cvtpk(float lo, float hi) { unsigned r; asm volatile("v_cvt_pk_bf16_f32 %0, %1, %2" : "=v"(r) : "v"(lo), "v"(hi)); return r; }
; template <int DKR, int LDQ, int LDK, int LDV, int LDO> ...
;     ...
;   for (int r = 0; r < 16; ++r) { int orow = crow(r, hi);
; #pragma unroll
;     for (int d0 = 0; d0 < 4; ++d0) Ow[(long)orow * LDO + d0 * 32 + r32] = (bf16_t)(cvtpk(o[d0][r] * rli[r], 0.f) & 0xffffu); }
	v_pk_mul_f32 v[114:115], v[114:115], v[96:97] op_sel_hi:[1,0]
	v_cvt_pk_bf16_f32 v73, v108, v109
	v_cvt_pk_bf16_f32 v116, v110, v111
	v_cvt_pk_bf16_f32 v117, v112, v113
	v_cvt_pk_bf16_f32 v118, v114, v115
	global_store_dword v[88:89], v73, off offset:2048
	global_store_dword v[88:89], v116, off offset:2112
	global_store_dword v[88:89], v117, off offset:2176
	global_store_dword v[88:89], v118, off offset:2240
	s_mov_b64 s[0:1], 0xa000
	v_lshl_add_u64 v[88:89], v[86:87], 0, s[0:1]
	s_mov_b32 vcc_lo, 0x55555555
	s_mov_b32 vcc_hi, 0x55555555
	s_nop 1
	v_cndmask_b32_dpp v108, v7, v6, vcc quad_perm:[1,0,3,2] row_mask:0xf bank_mask:0xf
	v_cndmask_b32_dpp v110, v55, v54, vcc quad_perm:[1,0,3,2] row_mask:0xf bank_mask:0xf
	v_cndmask_b32_dpp v112, v39, v38, vcc quad_perm:[1,0,3,2] row_mask:0xf bank_mask:0xf
	v_cndmask_b32_dpp v114, v23, v22, vcc quad_perm:[1,0,3,2] row_mask:0xf bank_mask:0xf
	s_mov_b32 vcc_lo, 0xaaaaaaaa
	s_mov_b32 vcc_hi, 0xaaaaaaaa
	s_nop 1
	v_cndmask_b32_dpp v109, v6, v7, vcc quad_perm:[1,0,3,2] row_mask:0xf bank_mask:0xf
	v_cndmask_b32_dpp v111, v54, v55, vcc quad_perm:[1,0,3,2] row_mask:0xf bank_mask:0xf
	v_cndmask_b32_dpp v113, v38, v39, vcc quad_perm:[1,0,3,2] row_mask:0xf bank_mask:0xf
	v_cndmask_b32_dpp v115, v22, v23, vcc quad_perm:[1,0,3,2] row_mask:0xf bank_mask:0xf
	v_pk_mul_f32 v[108:109], v[108:109], v[98:99] op_sel_hi:[1,0]
	v_pk_mul_f32 v[110:111], v[110:111], v[98:99] op_sel_hi:[1,0]
	v_pk_mul_f32 v[112:113], v[112:113], v[98:99] op_sel_hi:[1,0]
	v_pk_mul_f32 v[114:115], v[114:115], v[98:99] op_sel_hi:[1,0]
	v_cvt_pk_bf16_f32 v73, v108, v109
	v_cvt_pk_bf16_f32 v116, v110, v111
	v_cvt_pk_bf16_f32 v117, v112, v113
	v_cvt_pk_bf16_f32 v118, v114, v115
	global_store_dword v[88:89], v73, off offset:2048
	global_store_dword v[88:89], v116, off offset:2112
	global_store_dword v[88:89], v117, off offset:2176
	global_store_dword v[88:89], v118, off offset:2240
	s_mov_b64 s[0:1], 0x10000
	v_lshl_add_u64 v[88:89], v[86:87], 0, s[0:1]
	s_mov_b32 vcc_lo, 0x55555555
	s_mov_b32 vcc_hi, 0x55555555
	s_nop 1
	v_cndmask_b32_dpp v108, v9, v8, vcc quad_perm:[1,0,3,2] row_mask:0xf bank_mask:0xf
	v_cndmask_b32_dpp v110, v57, v56, vcc quad_perm:[1,0,3,2] row_mask:0xf bank_mask:0xf
	v_cndmask_b32_dpp v112, v41, v40, vcc quad_perm:[1,0,3,2] row_mask:0xf bank_mask:0xf
	v_cndmask_b32_dpp v114, v25, v24, vcc quad_perm:[1,0,3,2] row_mask:0xf bank_mask:0xf
	s_mov_b32 vcc_lo, 0xaaaaaaaa
	s_mov_b32 vcc_hi, 0xaaaaaaaa
	s_nop 1
	v_cndmask_b32_dpp v109, v8, v9, vcc quad_perm:[1,0,3,2] row_mask:0xf bank_mask:0xf
	v_cndmask_b32_dpp v111, v56, v57, vcc quad_perm:[1,0,3,2] row_mask:0xf bank_mask:0xf
	v_cndmask_b32_dpp v113, v40, v41, vcc quad_perm:[1,0,3,2] row_mask:0xf bank_mask:0xf
	v_cndmask_b32_dpp v115, v24, v25, vcc quad_perm:[1,0,3,2] row_mask:0xf bank_mask:0xf
	v_pk_mul_f32 v[108:109], v[108:109], v[100:101] op_sel_hi:[1,0]
	v_pk_mul_f32 v[110:111], v[110:111], v[100:101] op_sel_hi:[1,0]
	v_pk_mul_f32 v[112:113], v[112:113], v[100:101] op_sel_hi:[1,0]
	v_pk_mul_f32 v[114:115], v[114:115], v[100:101] op_sel_hi:[1,0]
	v_cvt_pk_bf16_f32 v73, v108, v109
	v_cvt_pk_bf16_f32 v116, v110, v111
	v_cvt_pk_bf16_f32 v117, v112, v113
	v_cvt_pk_bf16_f32 v118, v114, v115
	global_store_dword v[88:89], v73, off offset:2048
	global_store_dword v[88:89], v116, off offset:2112
	global_store_dword v[88:89], v117, off offset:2176
	global_store_dword v[88:89], v118, off offset:2240
	s_mov_b64 s[0:1], 0x12000
	v_lshl_add_u64 v[88:89], v[86:87], 0, s[0:1]
	s_mov_b32 vcc_lo, 0x55555555
	s_mov_b32 vcc_hi, 0x55555555
	s_nop 1
	v_cndmask_b32_dpp v108, v11, v10, vcc quad_perm:[1,0,3,2] row_mask:0xf bank_mask:0xf
	v_cndmask_b32_dpp v110, v59, v58, vcc quad_perm:[1,0,3,2] row_mask:0xf bank_mask:0xf
	v_cndmask_b32_dpp v112, v43, v42, vcc quad_perm:[1,0,3,2] row_mask:0xf bank_mask:0xf
	v_cndmask_b32_dpp v114, v27, v26, vcc quad_perm:[1,0,3,2] row_mask:0xf bank_mask:0xf
	s_mov_b32 vcc_lo, 0xaaaaaaaa
	s_mov_b32 vcc_hi, 0xaaaaaaaa
	s_nop 1
	v_cndmask_b32_dpp v109, v10, v11, vcc quad_perm:[1,0,3,2] row_mask:0xf bank_mask:0xf
; __device__ __forceinline__ int crow(int r, int hi) { return (r & 3) + 8 * (r >> 2) + 4 * hi; }
; __device__ __forceinline__ unsigned cvtpk(float lo, float hi) { unsigned r; asm volatile("v_cvt_pk_bf16_f32 %0, %1, %2" : "=v"(r) : "v"(lo), "v"(hi)); return r; }
; template <int DKR, int LDQ, int LDK, int LDV, int LDO> ...
;     ...
;   for (int r = 0; r < 16; ++r) { int orow = crow(r, hi);
; #pragma unroll
;     for (int d0 = 0; d0 < 4; ++d0) Ow[(long)orow * LDO + d0 * 32 + r32] = (bf16_t)(cvtpk(o[d0][r] * rli[r], 0.f) & 0xffffu); }
;   __syncthreads();
	v_cndmask_b32_dpp v111, v58, v59, vcc quad_perm:[1,0,3,2] row_mask:0xf bank_mask:0xf
	v_cndmask_b32_dpp v113, v42, v43, vcc quad_perm:[1,0,3,2] row_mask:0xf bank_mask:0xf
	v_cndmask_b32_dpp v115, v26, v27, vcc quad_perm:[1,0,3,2] row_mask:0xf bank_mask:0xf
	v_pk_mul_f32 v[108:109], v[108:109], v[102:103] op_sel_hi:[1,0]
	v_pk_mul_f32 v[110:111], v[110:111], v[102:103] op_sel_hi:[1,0]
	v_pk_mul_f32 v[112:113], v[112:113], v[102:103] op_sel_hi:[1,0]
	v_pk_mul_f32 v[114:115], v[114:115], v[102:103] op_sel_hi:[1,0]
	v_cvt_pk_bf16_f32 v73, v108, v109
	v_cvt_pk_bf16_f32 v116, v110, v111
	v_cvt_pk_bf16_f32 v117, v112, v113
	v_cvt_pk_bf16_f32 v118, v114, v115
	global_store_dword v[88:89], v73, off offset:2048
	global_store_dword v[88:89], v116, off offset:2112
	global_store_dword v[88:89], v117, off offset:2176
	global_store_dword v[88:89], v118, off offset:2240
	s_mov_b64 s[0:1], 0x18000
	v_lshl_add_u64 v[88:89], v[86:87], 0, s[0:1]
	s_mov_b32 vcc_lo, 0x55555555
	s_mov_b32 vcc_hi, 0x55555555
	s_nop 1
	v_cndmask_b32_dpp v108, v13, v12, vcc quad_perm:[1,0,3,2] row_mask:0xf bank_mask:0xf
	v_cndmask_b32_dpp v110, v61, v60, vcc quad_perm:[1,0,3,2] row_mask:0xf bank_mask:0xf
	v_cndmask_b32_dpp v112, v45, v44, vcc quad_perm:[1,0,3,2] row_mask:0xf bank_mask:0xf
	v_cndmask_b32_dpp v114, v29, v28, vcc quad_perm:[1,0,3,2] row_mask:0xf bank_mask:0xf
	s_mov_b32 vcc_lo, 0xaaaaaaaa
	s_mov_b32 vcc_hi, 0xaaaaaaaa
	s_nop 1
	v_cndmask_b32_dpp v109, v12, v13, vcc quad_perm:[1,0,3,2] row_mask:0xf bank_mask:0xf
	v_cndmask_b32_dpp v111, v60, v61, vcc quad_perm:[1,0,3,2] row_mask:0xf bank_mask:0xf
	v_cndmask_b32_dpp v113, v44, v45, vcc quad_perm:[1,0,3,2] row_mask:0xf bank_mask:0xf
	v_cndmask_b32_dpp v115, v28, v29, vcc quad_perm:[1,0,3,2] row_mask:0xf bank_mask:0xf
	v_pk_mul_f32 v[108:109], v[108:109], v[104:105] op_sel_hi:[1,0]
	v_pk_mul_f32 v[110:111], v[110:111], v[104:105] op_sel_hi:[1,0]
	v_pk_mul_f32 v[112:113], v[112:113], v[104:105] op_sel_hi:[1,0]
	v_pk_mul_f32 v[114:115], v[114:115], v[104:105] op_sel_hi:[1,0]
	v_cvt_pk_bf16_f32 v73, v108, v109
	v_cvt_pk_bf16_f32 v116, v110, v111
	v_cvt_pk_bf16_f32 v117, v112, v113
	v_cvt_pk_bf16_f32 v118, v114, v115
	global_store_dword v[88:89], v73, off offset:2048
	global_store_dword v[88:89], v116, off offset:2112
	global_store_dword v[88:89], v117, off offset:2176
	global_store_dword v[88:89], v118, off offset:2240
	s_mov_b64 s[0:1], 0x1a000
	v_lshl_add_u64 v[88:89], v[86:87], 0, s[0:1]
	s_mov_b32 vcc_lo, 0x55555555
	s_mov_b32 vcc_hi, 0x55555555
	s_nop 1
	v_cndmask_b32_dpp v108, v15, v14, vcc quad_perm:[1,0,3,2] row_mask:0xf bank_mask:0xf
	v_cndmask_b32_dpp v110, v63, v62, vcc quad_perm:[1,0,3,2] row_mask:0xf bank_mask:0xf
	v_cndmask_b32_dpp v112, v47, v46, vcc quad_perm:[1,0,3,2] row_mask:0xf bank_mask:0xf
	v_cndmask_b32_dpp v114, v31, v30, vcc quad_perm:[1,0,3,2] row_mask:0xf bank_mask:0xf
	s_mov_b32 vcc_lo, 0xaaaaaaaa
	s_mov_b32 vcc_hi, 0xaaaaaaaa
	s_nop 1
	v_cndmask_b32_dpp v109, v14, v15, vcc quad_perm:[1,0,3,2] row_mask:0xf bank_mask:0xf
	v_cndmask_b32_dpp v111, v62, v63, vcc quad_perm:[1,0,3,2] row_mask:0xf bank_mask:0xf
	v_cndmask_b32_dpp v113, v46, v47, vcc quad_perm:[1,0,3,2] row_mask:0xf bank_mask:0xf
	v_cndmask_b32_dpp v115, v30, v31, vcc quad_perm:[1,0,3,2] row_mask:0xf bank_mask:0xf
	v_pk_mul_f32 v[108:109], v[108:109], v[106:107] op_sel_hi:[1,0]
	v_pk_mul_f32 v[110:111], v[110:111], v[106:107] op_sel_hi:[1,0]
	v_pk_mul_f32 v[112:113], v[112:113], v[106:107] op_sel_hi:[1,0]
	v_pk_mul_f32 v[114:115], v[114:115], v[106:107] op_sel_hi:[1,0]
	v_cvt_pk_bf16_f32 v73, v108, v109
	v_cvt_pk_bf16_f32 v116, v110, v111
	v_cvt_pk_bf16_f32 v117, v112, v113
	v_cvt_pk_bf16_f32 v118, v114, v115
	global_store_dword v[88:89], v73, off offset:2048
	global_store_dword v[88:89], v116, off offset:2112
	global_store_dword v[88:89], v117, off offset:2176
	global_store_dword v[88:89], v118, off offset:2240
	s_mov_b32 s2, 4
	s_mov_b64 s[0:1], 0
	s_nop 1
	s_nop 1
	s_and_b64 vcc, exec, s[10:11]
	s_nop 0
	s_nop 0
	s_nop 0
	s_nop 0
	s_nop 0
	s_waitcnt vmcnt(63) expcnt(7) lgkmcnt(15)
	s_barrier
	s_cbranch_vccnz .LBB0_634
